# hand-written software-pipelined phase_norm and phase_final row loops (prefetch next row, gains hoisted)
# baseline (speedup 1.0000x reference)
; __device__ __forceinline__ void phase_norm(PP p, int l, const float* mod, int lane, int wave) {
;     const float* xin = (l == 0) ? p->x : p->out;
;     bf16_t* H = (bf16_t*)(p->ws + WS_H);
;     const float* ng = p->norm_g + (size_t)l * DM;
;     const float* modl = mod + (size_t)l * 4 * NMOD;
;     const int gw = blockIdx.x * 8 + wave, NGW = gridDim.x * 8;
;     for (int row = gw; row < MTOK; row += NGW) {
;         const int b = row >> 12;
;         const f32x4* xr = (const f32x4*)(xin + (size_t)row * DM) + lane;
;         f32x4 v[8]; float s = 0.f;
; #pragma unroll
;         for (int j = 0; j < 8; ++j) { v[j] = xr[64 * j]; s += (v[j].x * v[j].x + v[j].y * v[j].y) + (v[j].z * v[j].z + v[j].w * v[j].w); }
;         s = wave_sum(s);
.LBB0_135:
	s_mov_b64 s[2:3], s[68:69]
	s_mov_b32 s4, s80
	s_add_i32 s4, s4, s81
	s_mov_b32 s5, s77
	s_cmpk_gt_i32 s4, 0x3fff
	s_mul_i32 s16, s60, 0x18000
	s_cbranch_scc1 .LBB0_138
	s_load_dwordx2 s[10:11], s[68:69], 0x88
	s_load_dwordx2 s[12:13], s[68:69], 0x10
	s_cmp_eq_u32 s60, 0
	s_cselect_b32 s5, 0, 0x80
	s_add_u32 s2, s68, s5
	s_addc_u32 s3, s69, 0
	v_lshlrev_b32_e32 v160, 4, v239
	v_lshlrev_b32_e32 v161, 3, v239
	v_xor_b32_e32 v162, 1, v239
	v_xor_b32_e32 v163, 2, v239
	v_xor_b32_e32 v164, 4, v239
	v_xor_b32_e32 v165, 8, v239
	v_xor_b32_e32 v166, 16, v239
	v_xor_b32_e32 v167, 32, v239
	v_lshlrev_b32_e32 v162, 2, v162
	v_lshlrev_b32_e32 v163, 2, v163
	v_lshlrev_b32_e32 v164, 2, v164
	v_lshlrev_b32_e32 v165, 2, v165
	v_lshlrev_b32_e32 v166, 2, v166
	v_lshlrev_b32_e32 v167, 2, v167
	s_load_dwordx2 s[2:3], s[2:3], 0x0
	s_waitcnt lgkmcnt(0)
	s_add_u32 s6, s10, s16
	s_addc_u32 s7, s11, 0
	s_add_u32 s6, s6, 0x2000
	s_addc_u32 s7, s7, 0
	s_add_u32 s8, s10, 0x7100000
	s_addc_u32 s9, s11, 0
	s_lshl_b32 s5, s60, 13
	s_add_u32 s12, s12, s5
	s_addc_u32 s13, s13, 0
	s_add_u32 s12, s12, 0x1000
	s_addc_u32 s13, s13, 0
	s_add_u32 s2, s2, 0x1000
	s_addc_u32 s3, s3, 0
	s_lshl_b32 s5, s4, 13
	s_add_u32 s14, s2, s5
	s_addc_u32 s15, s3, 0
	global_load_dwordx4 v[0:3], v160, s[14:15] offset:-4096
	global_load_dwordx4 v[4:7], v160, s[14:15] offset:-3072
	global_load_dwordx4 v[8:11], v160, s[14:15] offset:-2048
	global_load_dwordx4 v[12:15], v160, s[14:15] offset:-1024
	global_load_dwordx4 v[16:19], v160, s[14:15] offset:0
	global_load_dwordx4 v[20:23], v160, s[14:15] offset:1024
	global_load_dwordx4 v[24:27], v160, s[14:15] offset:2048
	global_load_dwordx4 v[28:31], v160, s[14:15] offset:3072
	global_load_dwordx4 v[64:67], v160, s[12:13] offset:-4096
	global_load_dwordx4 v[68:71], v160, s[12:13] offset:-3072
	global_load_dwordx4 v[72:75], v160, s[12:13] offset:-2048
	global_load_dwordx4 v[76:79], v160, s[12:13] offset:-1024
	global_load_dwordx4 v[80:83], v160, s[12:13] offset:0
	global_load_dwordx4 v[84:87], v160, s[12:13] offset:1024
	global_load_dwordx4 v[88:91], v160, s[12:13] offset:2048
	global_load_dwordx4 v[92:95], v160, s[12:13] offset:3072
	s_mov_b32 s98, -1
.Lhn_it_a:
	s_add_i32 s5, s4, s74
	s_cmp_lt_i32 s5, 0x4000
	s_cselect_b32 s99, s5, s4
	s_lshl_b32 s99, s99, 13
	s_add_u32 s14, s2, s99
	s_addc_u32 s15, s3, 0
	s_lshr_b32 s100, s4, 12
	s_cmp_eq_u32 s100, s98
	s_cbranch_scc1 .Lhn_nomod_a
	s_mul_i32 s101, s100, 0x6000
	s_add_u32 s12, s6, s101
	s_addc_u32 s13, s7, 0
	s_mov_b32 s98, s100
	global_load_dwordx4 v[128:131], v160, s[12:13] offset:-4096
	global_load_dwordx4 v[132:135], v160, s[12:13] offset:-3072
	global_load_dwordx4 v[136:139], v160, s[12:13] offset:-2048
	global_load_dwordx4 v[140:143], v160, s[12:13] offset:-1024
	global_load_dwordx4 v[144:147], v160, s[12:13] offset:0
	global_load_dwordx4 v[148:151], v160, s[12:13] offset:1024
	global_load_dwordx4 v[152:155], v160, s[12:13] offset:2048
	global_load_dwordx4 v[156:159], v160, s[12:13] offset:3072
	s_add_u32 s12, s12, 0x2000
	s_addc_u32 s13, s13, 0
	global_load_dwordx4 v[96:99], v160, s[12:13] offset:-4096
	global_load_dwordx4 v[100:103], v160, s[12:13] offset:-3072
	global_load_dwordx4 v[104:107], v160, s[12:13] offset:-2048
	global_load_dwordx4 v[108:111], v160, s[12:13] offset:-1024
	global_load_dwordx4 v[112:115], v160, s[12:13] offset:0
	global_load_dwordx4 v[116:119], v160, s[12:13] offset:1024
	global_load_dwordx4 v[120:123], v160, s[12:13] offset:2048
	global_load_dwordx4 v[124:127], v160, s[12:13] offset:3072
	global_load_dwordx4 v[32:35], v160, s[14:15] offset:-4096
	global_load_dwordx4 v[36:39], v160, s[14:15] offset:-3072
	global_load_dwordx4 v[40:43], v160, s[14:15] offset:-2048
	global_load_dwordx4 v[44:47], v160, s[14:15] offset:-1024
	global_load_dwordx4 v[48:51], v160, s[14:15] offset:0
	global_load_dwordx4 v[52:55], v160, s[14:15] offset:1024
	global_load_dwordx4 v[56:59], v160, s[14:15] offset:2048
	global_load_dwordx4 v[60:63], v160, s[14:15] offset:3072
	s_waitcnt vmcnt(32)
	v_pk_mul_f32 v[168:169], v[0:1], v[0:1]
	v_pk_mul_f32 v[170:171], v[2:3], v[2:3]
	v_pk_fma_f32 v[168:169], v[4:5], v[4:5], v[168:169]
	v_pk_fma_f32 v[170:171], v[6:7], v[6:7], v[170:171]
	v_pk_fma_f32 v[168:169], v[8:9], v[8:9], v[168:169]
	v_pk_fma_f32 v[170:171], v[10:11], v[10:11], v[170:171]
	v_pk_fma_f32 v[168:169], v[12:13], v[12:13], v[168:169]
	v_pk_fma_f32 v[170:171], v[14:15], v[14:15], v[170:171]
	v_pk_fma_f32 v[168:169], v[16:17], v[16:17], v[168:169]
	v_pk_fma_f32 v[170:171], v[18:19], v[18:19], v[170:171]
	v_pk_fma_f32 v[168:169], v[20:21], v[20:21], v[168:169]
	v_pk_fma_f32 v[170:171], v[22:23], v[22:23], v[170:171]
	v_pk_fma_f32 v[168:169], v[24:25], v[24:25], v[168:169]
	v_pk_fma_f32 v[170:171], v[26:27], v[26:27], v[170:171]
	v_pk_fma_f32 v[168:169], v[28:29], v[28:29], v[168:169]
	v_pk_fma_f32 v[170:171], v[30:31], v[30:31], v[170:171]
	s_nop 0
	v_pk_add_f32 v[168:169], v[168:169], v[170:171]
	s_nop 0
	v_add_f32_e32 v168, v168, v169
	ds_bpermute_b32 v169, v162, v168
	s_waitcnt lgkmcnt(0)
	v_add_f32_e32 v168, v168, v169
	ds_bpermute_b32 v169, v163, v168
	s_waitcnt lgkmcnt(0)
	v_add_f32_e32 v168, v168, v169
	ds_bpermute_b32 v169, v164, v168
	s_waitcnt lgkmcnt(0)
	v_add_f32_e32 v168, v168, v169
	ds_bpermute_b32 v169, v165, v168
	s_waitcnt lgkmcnt(0)
	v_add_f32_e32 v168, v168, v169
	ds_bpermute_b32 v169, v166, v168
	s_waitcnt lgkmcnt(0)
	v_add_f32_e32 v168, v168, v169
	ds_bpermute_b32 v169, v167, v168
	s_waitcnt lgkmcnt(0)
; __device__ __forceinline__ void phase_norm(PP p, int l, const float* mod, int lane, int wave) {
;     ...
;         s = wave_sum(s);
;         const float rstd = 1.f / sqrtf(s * (1.f / DM) + RMS_EPS);
;         u32x2* o8 = (u32x2*)(H + (size_t)row * DM) + lane;
; #pragma unroll
;         for (int j = 0; j < 8; ++j) { const int col = 4 * lane + 256 * j;
;             const f32x4 g4 = *(const f32x4*)(ng + col), sh = *(const f32x4*)(modl + (size_t)b * NMOD + col), sc = *(const f32x4*)(modl + (size_t)b * NMOD + DM + col);
	v_add_f32_e32 v168, v168, v169
	v_mov_b32_e32 v169, 0x358637bd
	v_fmamk_f32 v168, v168, 0x3a000000, v169
	v_cmp_gt_f32_e32 vcc, 0xf800000, v168
	v_mul_f32_e32 v169, 0x4f800000, v168
	s_nop 0
	v_cndmask_b32_e32 v168, v168, v169, vcc
	v_sqrt_f32_e32 v169, v168
	s_nop 0
	v_add_u32_e32 v170, -1, v169
	v_fma_f32 v171, -v170, v169, v168
	v_cmp_ge_f32_e64 s[100:101], 0, v171
	v_add_u32_e32 v171, 1, v169
	s_nop 0
	v_cndmask_b32_e64 v170, v169, v170, s[100:101]
	v_fma_f32 v169, -v171, v169, v168
	v_cmp_lt_f32_e64 s[100:101], 0, v169
	s_nop 1
	v_cndmask_b32_e64 v169, v170, v171, s[100:101]
	v_mul_f32_e32 v170, 0x37800000, v169
	v_cndmask_b32_e32 v169, v169, v170, vcc
	v_mov_b32_e32 v170, 0x260
	v_cmp_class_f32_e32 vcc, v168, v170
	s_nop 1
	v_cndmask_b32_e32 v168, v169, v168, vcc
	v_div_scale_f32 v169, s[100:101], v168, v168, 1.0
	v_rcp_f32_e32 v170, v169
	s_nop 0
	v_fma_f32 v171, -v169, v170, 1.0
	v_fmac_f32_e32 v170, v171, v170
	v_div_scale_f32 v171, vcc, 1.0, v168, 1.0
	v_mul_f32_e32 v172, v171, v170
	v_fma_f32 v173, -v169, v172, v171
	v_fmac_f32_e32 v172, v173, v170
	v_fma_f32 v169, -v169, v172, v171
	s_nop 0
	v_div_fmas_f32 v169, v169, v170, v172
	v_div_fixup_f32 v172, v169, v168, 1.0
	s_waitcnt vmcnt(8)
	v_pk_add_f32 v[96:97], v[96:97], 1.0 op_sel_hi:[1,0]
	v_pk_add_f32 v[98:99], v[98:99], 1.0 op_sel_hi:[1,0]
	v_pk_add_f32 v[100:101], v[100:101], 1.0 op_sel_hi:[1,0]
	v_pk_add_f32 v[102:103], v[102:103], 1.0 op_sel_hi:[1,0]
	v_pk_add_f32 v[104:105], v[104:105], 1.0 op_sel_hi:[1,0]
	v_pk_add_f32 v[106:107], v[106:107], 1.0 op_sel_hi:[1,0]
	v_pk_add_f32 v[108:109], v[108:109], 1.0 op_sel_hi:[1,0]
	v_pk_add_f32 v[110:111], v[110:111], 1.0 op_sel_hi:[1,0]
	v_pk_add_f32 v[112:113], v[112:113], 1.0 op_sel_hi:[1,0]
	v_pk_add_f32 v[114:115], v[114:115], 1.0 op_sel_hi:[1,0]
	v_pk_add_f32 v[116:117], v[116:117], 1.0 op_sel_hi:[1,0]
	v_pk_add_f32 v[118:119], v[118:119], 1.0 op_sel_hi:[1,0]
	v_pk_add_f32 v[120:121], v[120:121], 1.0 op_sel_hi:[1,0]
	v_pk_add_f32 v[122:123], v[122:123], 1.0 op_sel_hi:[1,0]
	v_pk_add_f32 v[124:125], v[124:125], 1.0 op_sel_hi:[1,0]
	v_pk_add_f32 v[126:127], v[126:127], 1.0 op_sel_hi:[1,0]
	s_branch .Lhn_comp_a
.Lhn_nomod_a:
	global_load_dwordx4 v[32:35], v160, s[14:15] offset:-4096
	global_load_dwordx4 v[36:39], v160, s[14:15] offset:-3072
	global_load_dwordx4 v[40:43], v160, s[14:15] offset:-2048
	global_load_dwordx4 v[44:47], v160, s[14:15] offset:-1024
	global_load_dwordx4 v[48:51], v160, s[14:15] offset:0
	global_load_dwordx4 v[52:55], v160, s[14:15] offset:1024
	global_load_dwordx4 v[56:59], v160, s[14:15] offset:2048
	global_load_dwordx4 v[60:63], v160, s[14:15] offset:3072
	s_waitcnt vmcnt(16)
	v_pk_mul_f32 v[168:169], v[0:1], v[0:1]
	v_pk_mul_f32 v[170:171], v[2:3], v[2:3]
	v_pk_fma_f32 v[168:169], v[4:5], v[4:5], v[168:169]
	v_pk_fma_f32 v[170:171], v[6:7], v[6:7], v[170:171]
	v_pk_fma_f32 v[168:169], v[8:9], v[8:9], v[168:169]
	v_pk_fma_f32 v[170:171], v[10:11], v[10:11], v[170:171]
	v_pk_fma_f32 v[168:169], v[12:13], v[12:13], v[168:169]
	v_pk_fma_f32 v[170:171], v[14:15], v[14:15], v[170:171]
	v_pk_fma_f32 v[168:169], v[16:17], v[16:17], v[168:169]
	v_pk_fma_f32 v[170:171], v[18:19], v[18:19], v[170:171]
	v_pk_fma_f32 v[168:169], v[20:21], v[20:21], v[168:169]
	v_pk_fma_f32 v[170:171], v[22:23], v[22:23], v[170:171]
	v_pk_fma_f32 v[168:169], v[24:25], v[24:25], v[168:169]
	v_pk_fma_f32 v[170:171], v[26:27], v[26:27], v[170:171]
	v_pk_fma_f32 v[168:169], v[28:29], v[28:29], v[168:169]
	v_pk_fma_f32 v[170:171], v[30:31], v[30:31], v[170:171]
	s_nop 0
	v_pk_add_f32 v[168:169], v[168:169], v[170:171]
	s_nop 0
	v_add_f32_e32 v168, v168, v169
	ds_bpermute_b32 v169, v162, v168
	s_waitcnt lgkmcnt(0)
	v_add_f32_e32 v168, v168, v169
	ds_bpermute_b32 v169, v163, v168
	s_waitcnt lgkmcnt(0)
	v_add_f32_e32 v168, v168, v169
	ds_bpermute_b32 v169, v164, v168
	s_waitcnt lgkmcnt(0)
	v_add_f32_e32 v168, v168, v169
	ds_bpermute_b32 v169, v165, v168
	s_waitcnt lgkmcnt(0)
	v_add_f32_e32 v168, v168, v169
	ds_bpermute_b32 v169, v166, v168
	s_waitcnt lgkmcnt(0)
	v_add_f32_e32 v168, v168, v169
	ds_bpermute_b32 v169, v167, v168
	s_waitcnt lgkmcnt(0)
	v_add_f32_e32 v168, v168, v169
	v_mov_b32_e32 v169, 0x358637bd
	v_fmamk_f32 v168, v168, 0x3a000000, v169
	v_cmp_gt_f32_e32 vcc, 0xf800000, v168
	v_mul_f32_e32 v169, 0x4f800000, v168
	s_nop 0
	v_cndmask_b32_e32 v168, v168, v169, vcc
	v_sqrt_f32_e32 v169, v168
	s_nop 0
	v_add_u32_e32 v170, -1, v169
	v_fma_f32 v171, -v170, v169, v168
	v_cmp_ge_f32_e64 s[100:101], 0, v171
	v_add_u32_e32 v171, 1, v169
	s_nop 0
	v_cndmask_b32_e64 v170, v169, v170, s[100:101]
	v_fma_f32 v169, -v171, v169, v168
	v_cmp_lt_f32_e64 s[100:101], 0, v169
	s_nop 1
	v_cndmask_b32_e64 v169, v170, v171, s[100:101]
	v_mul_f32_e32 v170, 0x37800000, v169
	v_cndmask_b32_e32 v169, v169, v170, vcc
	v_mov_b32_e32 v170, 0x260
	v_cmp_class_f32_e32 vcc, v168, v170
	s_nop 1
	v_cndmask_b32_e32 v168, v169, v168, vcc
	v_div_scale_f32 v169, s[100:101], v168, v168, 1.0
	v_rcp_f32_e32 v170, v169
	s_nop 0
	v_fma_f32 v171, -v169, v170, 1.0
	v_fmac_f32_e32 v170, v171, v170
	v_div_scale_f32 v171, vcc, 1.0, v168, 1.0
	v_mul_f32_e32 v172, v171, v170
	v_fma_f32 v173, -v169, v172, v171
	v_fmac_f32_e32 v172, v173, v170
	v_fma_f32 v169, -v169, v172, v171
	s_nop 0
	v_div_fmas_f32 v169, v169, v170, v172
	v_div_fixup_f32 v172, v169, v168, 1.0
; __device__ __forceinline__ void phase_norm(PP p, int l, const float* mod, int lane, int wave) {
;     ...
;     for (int row = gw; row < MTOK; row += NGW) {
;         const int b = row >> 12;
;         const f32x4* xr = (const f32x4*)(xin + (size_t)row * DM) + lane;
;         f32x4 v[8]; float s = 0.f;
; #pragma unroll
;         for (int j = 0; j < 8; ++j) { v[j] = xr[64 * j]; s += (v[j].x * v[j].x + v[j].y * v[j].y) + (v[j].z * v[j].z + v[j].w * v[j].w); }
;         s = wave_sum(s);
;         const float rstd = 1.f / sqrtf(s * (1.f / DM) + RMS_EPS);
;         u32x2* o8 = (u32x2*)(H + (size_t)row * DM) + lane;
; #pragma unroll
;         for (int j = 0; j < 8; ++j) { const int col = 4 * lane + 256 * j;
;             const f32x4 g4 = *(const f32x4*)(ng + col), sh = *(const f32x4*)(modl + (size_t)b * NMOD + col), sc = *(const f32x4*)(modl + (size_t)b * NMOD + DM + col);
;             const f32x4 y = v[j] * rstd * g4 * (sc + 1.f) + sh;
;             u32x2 w; w.x = cvtpk(y.x, y.y); w.y = cvtpk(y.z, y.w); o8[64 * j] = w; }
.Lhn_comp_a:
	s_lshl_b32 s101, s4, 12
	s_add_u32 s12, s8, s101
	s_addc_u32 s13, s9, 0
	v_pk_mul_f32 v[0:1], v[0:1], v[172:173] op_sel_hi:[1,0]
	v_pk_mul_f32 v[2:3], v[2:3], v[172:173] op_sel_hi:[1,0]
	v_pk_mul_f32 v[0:1], v[64:65], v[0:1]
	v_pk_mul_f32 v[2:3], v[66:67], v[2:3]
	v_pk_fma_f32 v[0:1], v[96:97], v[0:1], v[128:129]
	v_pk_fma_f32 v[2:3], v[98:99], v[2:3], v[130:131]
	s_nop 0
	v_cvt_pk_bf16_f32 v0, v0, v1
	v_cvt_pk_bf16_f32 v1, v2, v3
	global_store_dwordx2 v161, v[0:1], s[12:13] offset:0
	v_pk_mul_f32 v[4:5], v[4:5], v[172:173] op_sel_hi:[1,0]
	v_pk_mul_f32 v[6:7], v[6:7], v[172:173] op_sel_hi:[1,0]
	v_pk_mul_f32 v[4:5], v[68:69], v[4:5]
	v_pk_mul_f32 v[6:7], v[70:71], v[6:7]
	v_pk_fma_f32 v[4:5], v[100:101], v[4:5], v[132:133]
	v_pk_fma_f32 v[6:7], v[102:103], v[6:7], v[134:135]
	s_nop 0
	v_cvt_pk_bf16_f32 v4, v4, v5
	v_cvt_pk_bf16_f32 v5, v6, v7
	global_store_dwordx2 v161, v[4:5], s[12:13] offset:512
	v_pk_mul_f32 v[8:9], v[8:9], v[172:173] op_sel_hi:[1,0]
	v_pk_mul_f32 v[10:11], v[10:11], v[172:173] op_sel_hi:[1,0]
	v_pk_mul_f32 v[8:9], v[72:73], v[8:9]
	v_pk_mul_f32 v[10:11], v[74:75], v[10:11]
	v_pk_fma_f32 v[8:9], v[104:105], v[8:9], v[136:137]
	v_pk_fma_f32 v[10:11], v[106:107], v[10:11], v[138:139]
	s_nop 0
	v_cvt_pk_bf16_f32 v8, v8, v9
	v_cvt_pk_bf16_f32 v9, v10, v11
	global_store_dwordx2 v161, v[8:9], s[12:13] offset:1024
	v_pk_mul_f32 v[12:13], v[12:13], v[172:173] op_sel_hi:[1,0]
	v_pk_mul_f32 v[14:15], v[14:15], v[172:173] op_sel_hi:[1,0]
	v_pk_mul_f32 v[12:13], v[76:77], v[12:13]
	v_pk_mul_f32 v[14:15], v[78:79], v[14:15]
	v_pk_fma_f32 v[12:13], v[108:109], v[12:13], v[140:141]
	v_pk_fma_f32 v[14:15], v[110:111], v[14:15], v[142:143]
	s_nop 0
	v_cvt_pk_bf16_f32 v12, v12, v13
	v_cvt_pk_bf16_f32 v13, v14, v15
	global_store_dwordx2 v161, v[12:13], s[12:13] offset:1536
	v_pk_mul_f32 v[16:17], v[16:17], v[172:173] op_sel_hi:[1,0]
	v_pk_mul_f32 v[18:19], v[18:19], v[172:173] op_sel_hi:[1,0]
	v_pk_mul_f32 v[16:17], v[80:81], v[16:17]
	v_pk_mul_f32 v[18:19], v[82:83], v[18:19]
	v_pk_fma_f32 v[16:17], v[112:113], v[16:17], v[144:145]
	v_pk_fma_f32 v[18:19], v[114:115], v[18:19], v[146:147]
	s_nop 0
	v_cvt_pk_bf16_f32 v16, v16, v17
	v_cvt_pk_bf16_f32 v17, v18, v19
	global_store_dwordx2 v161, v[16:17], s[12:13] offset:2048
	v_pk_mul_f32 v[20:21], v[20:21], v[172:173] op_sel_hi:[1,0]
	v_pk_mul_f32 v[22:23], v[22:23], v[172:173] op_sel_hi:[1,0]
	v_pk_mul_f32 v[20:21], v[84:85], v[20:21]
	v_pk_mul_f32 v[22:23], v[86:87], v[22:23]
	v_pk_fma_f32 v[20:21], v[116:117], v[20:21], v[148:149]
	v_pk_fma_f32 v[22:23], v[118:119], v[22:23], v[150:151]
	s_nop 0
	v_cvt_pk_bf16_f32 v20, v20, v21
	v_cvt_pk_bf16_f32 v21, v22, v23
	global_store_dwordx2 v161, v[20:21], s[12:13] offset:2560
	v_pk_mul_f32 v[24:25], v[24:25], v[172:173] op_sel_hi:[1,0]
	v_pk_mul_f32 v[26:27], v[26:27], v[172:173] op_sel_hi:[1,0]
	v_pk_mul_f32 v[24:25], v[88:89], v[24:25]
	v_pk_mul_f32 v[26:27], v[90:91], v[26:27]
	v_pk_fma_f32 v[24:25], v[120:121], v[24:25], v[152:153]
	v_pk_fma_f32 v[26:27], v[122:123], v[26:27], v[154:155]
	s_nop 0
	v_cvt_pk_bf16_f32 v24, v24, v25
	v_cvt_pk_bf16_f32 v25, v26, v27
	global_store_dwordx2 v161, v[24:25], s[12:13] offset:3072
	v_pk_mul_f32 v[28:29], v[28:29], v[172:173] op_sel_hi:[1,0]
	v_pk_mul_f32 v[30:31], v[30:31], v[172:173] op_sel_hi:[1,0]
	v_pk_mul_f32 v[28:29], v[92:93], v[28:29]
	v_pk_mul_f32 v[30:31], v[94:95], v[30:31]
	v_pk_fma_f32 v[28:29], v[124:125], v[28:29], v[156:157]
	v_pk_fma_f32 v[30:31], v[126:127], v[30:31], v[158:159]
	s_nop 0
	v_cvt_pk_bf16_f32 v28, v28, v29
	v_cvt_pk_bf16_f32 v29, v30, v31
	global_store_dwordx2 v161, v[28:29], s[12:13] offset:3584
	s_mov_b32 s4, s5
	s_cmp_lt_i32 s4, 0x4000
	s_cbranch_scc0 .Lhn_done
.Lhn_it_b:
	s_add_i32 s5, s4, s74
	s_cmp_lt_i32 s5, 0x4000
	s_cselect_b32 s99, s5, s4
	s_lshl_b32 s99, s99, 13
	s_add_u32 s14, s2, s99
	s_addc_u32 s15, s3, 0
	s_lshr_b32 s100, s4, 12
	s_cmp_eq_u32 s100, s98
	s_cbranch_scc1 .Lhn_nomod_b
	s_mul_i32 s101, s100, 0x6000
	s_add_u32 s12, s6, s101
	s_addc_u32 s13, s7, 0
	s_mov_b32 s98, s100
	global_load_dwordx4 v[128:131], v160, s[12:13] offset:-4096
	global_load_dwordx4 v[132:135], v160, s[12:13] offset:-3072
	global_load_dwordx4 v[136:139], v160, s[12:13] offset:-2048
	global_load_dwordx4 v[140:143], v160, s[12:13] offset:-1024
	global_load_dwordx4 v[144:147], v160, s[12:13] offset:0
	global_load_dwordx4 v[148:151], v160, s[12:13] offset:1024
	global_load_dwordx4 v[152:155], v160, s[12:13] offset:2048
	global_load_dwordx4 v[156:159], v160, s[12:13] offset:3072
	s_add_u32 s12, s12, 0x2000
	s_addc_u32 s13, s13, 0
	global_load_dwordx4 v[96:99], v160, s[12:13] offset:-4096
	global_load_dwordx4 v[100:103], v160, s[12:13] offset:-3072
	global_load_dwordx4 v[104:107], v160, s[12:13] offset:-2048
	global_load_dwordx4 v[108:111], v160, s[12:13] offset:-1024
	global_load_dwordx4 v[112:115], v160, s[12:13] offset:0
	global_load_dwordx4 v[116:119], v160, s[12:13] offset:1024
	global_load_dwordx4 v[120:123], v160, s[12:13] offset:2048
	global_load_dwordx4 v[124:127], v160, s[12:13] offset:3072
	global_load_dwordx4 v[0:3], v160, s[14:15] offset:-4096
	global_load_dwordx4 v[4:7], v160, s[14:15] offset:-3072
	global_load_dwordx4 v[8:11], v160, s[14:15] offset:-2048
	global_load_dwordx4 v[12:15], v160, s[14:15] offset:-1024
	global_load_dwordx4 v[16:19], v160, s[14:15] offset:0
	global_load_dwordx4 v[20:23], v160, s[14:15] offset:1024
	global_load_dwordx4 v[24:27], v160, s[14:15] offset:2048
	global_load_dwordx4 v[28:31], v160, s[14:15] offset:3072
	s_waitcnt vmcnt(32)
; __device__ __forceinline__ void phase_norm(PP p, int l, const float* mod, int lane, int wave) {
;     ...
;         for (int j = 0; j < 8; ++j) { v[j] = xr[64 * j]; s += (v[j].x * v[j].x + v[j].y * v[j].y) + (v[j].z * v[j].z + v[j].w * v[j].w); }
;         s = wave_sum(s);
;         const float rstd = 1.f / sqrtf(s * (1.f / DM) + RMS_EPS);
	v_pk_mul_f32 v[168:169], v[32:33], v[32:33]
	v_pk_mul_f32 v[170:171], v[34:35], v[34:35]
	v_pk_fma_f32 v[168:169], v[36:37], v[36:37], v[168:169]
	v_pk_fma_f32 v[170:171], v[38:39], v[38:39], v[170:171]
	v_pk_fma_f32 v[168:169], v[40:41], v[40:41], v[168:169]
	v_pk_fma_f32 v[170:171], v[42:43], v[42:43], v[170:171]
	v_pk_fma_f32 v[168:169], v[44:45], v[44:45], v[168:169]
	v_pk_fma_f32 v[170:171], v[46:47], v[46:47], v[170:171]
	v_pk_fma_f32 v[168:169], v[48:49], v[48:49], v[168:169]
	v_pk_fma_f32 v[170:171], v[50:51], v[50:51], v[170:171]
	v_pk_fma_f32 v[168:169], v[52:53], v[52:53], v[168:169]
	v_pk_fma_f32 v[170:171], v[54:55], v[54:55], v[170:171]
	v_pk_fma_f32 v[168:169], v[56:57], v[56:57], v[168:169]
	v_pk_fma_f32 v[170:171], v[58:59], v[58:59], v[170:171]
	v_pk_fma_f32 v[168:169], v[60:61], v[60:61], v[168:169]
	v_pk_fma_f32 v[170:171], v[62:63], v[62:63], v[170:171]
	s_nop 0
	v_pk_add_f32 v[168:169], v[168:169], v[170:171]
	s_nop 0
	v_add_f32_e32 v168, v168, v169
	ds_bpermute_b32 v169, v162, v168
	s_waitcnt lgkmcnt(0)
	v_add_f32_e32 v168, v168, v169
	ds_bpermute_b32 v169, v163, v168
	s_waitcnt lgkmcnt(0)
	v_add_f32_e32 v168, v168, v169
	ds_bpermute_b32 v169, v164, v168
	s_waitcnt lgkmcnt(0)
	v_add_f32_e32 v168, v168, v169
	ds_bpermute_b32 v169, v165, v168
	s_waitcnt lgkmcnt(0)
	v_add_f32_e32 v168, v168, v169
	ds_bpermute_b32 v169, v166, v168
	s_waitcnt lgkmcnt(0)
	v_add_f32_e32 v168, v168, v169
	ds_bpermute_b32 v169, v167, v168
	s_waitcnt lgkmcnt(0)
	v_add_f32_e32 v168, v168, v169
	v_mov_b32_e32 v169, 0x358637bd
	v_fmamk_f32 v168, v168, 0x3a000000, v169
	v_cmp_gt_f32_e32 vcc, 0xf800000, v168
	v_mul_f32_e32 v169, 0x4f800000, v168
	s_nop 0
	v_cndmask_b32_e32 v168, v168, v169, vcc
	v_sqrt_f32_e32 v169, v168
	s_nop 0
	v_add_u32_e32 v170, -1, v169
	v_fma_f32 v171, -v170, v169, v168
	v_cmp_ge_f32_e64 s[100:101], 0, v171
	v_add_u32_e32 v171, 1, v169
	s_nop 0
	v_cndmask_b32_e64 v170, v169, v170, s[100:101]
	v_fma_f32 v169, -v171, v169, v168
	v_cmp_lt_f32_e64 s[100:101], 0, v169
	s_nop 1
	v_cndmask_b32_e64 v169, v170, v171, s[100:101]
	v_mul_f32_e32 v170, 0x37800000, v169
	v_cndmask_b32_e32 v169, v169, v170, vcc
	v_mov_b32_e32 v170, 0x260
	v_cmp_class_f32_e32 vcc, v168, v170
	s_nop 1
	v_cndmask_b32_e32 v168, v169, v168, vcc
	v_div_scale_f32 v169, s[100:101], v168, v168, 1.0
	v_rcp_f32_e32 v170, v169
	s_nop 0
	v_fma_f32 v171, -v169, v170, 1.0
	v_fmac_f32_e32 v170, v171, v170
	v_div_scale_f32 v171, vcc, 1.0, v168, 1.0
	v_mul_f32_e32 v172, v171, v170
	v_fma_f32 v173, -v169, v172, v171
	v_fmac_f32_e32 v172, v173, v170
	v_fma_f32 v169, -v169, v172, v171
	s_nop 0
	v_div_fmas_f32 v169, v169, v170, v172
	v_div_fixup_f32 v172, v169, v168, 1.0
	s_waitcnt vmcnt(8)
	v_pk_add_f32 v[96:97], v[96:97], 1.0 op_sel_hi:[1,0]
	v_pk_add_f32 v[98:99], v[98:99], 1.0 op_sel_hi:[1,0]
	v_pk_add_f32 v[100:101], v[100:101], 1.0 op_sel_hi:[1,0]
	v_pk_add_f32 v[102:103], v[102:103], 1.0 op_sel_hi:[1,0]
	v_pk_add_f32 v[104:105], v[104:105], 1.0 op_sel_hi:[1,0]
	v_pk_add_f32 v[106:107], v[106:107], 1.0 op_sel_hi:[1,0]
	v_pk_add_f32 v[108:109], v[108:109], 1.0 op_sel_hi:[1,0]
	v_pk_add_f32 v[110:111], v[110:111], 1.0 op_sel_hi:[1,0]
	v_pk_add_f32 v[112:113], v[112:113], 1.0 op_sel_hi:[1,0]
	v_pk_add_f32 v[114:115], v[114:115], 1.0 op_sel_hi:[1,0]
	v_pk_add_f32 v[116:117], v[116:117], 1.0 op_sel_hi:[1,0]
	v_pk_add_f32 v[118:119], v[118:119], 1.0 op_sel_hi:[1,0]
	v_pk_add_f32 v[120:121], v[120:121], 1.0 op_sel_hi:[1,0]
	v_pk_add_f32 v[122:123], v[122:123], 1.0 op_sel_hi:[1,0]
	v_pk_add_f32 v[124:125], v[124:125], 1.0 op_sel_hi:[1,0]
	v_pk_add_f32 v[126:127], v[126:127], 1.0 op_sel_hi:[1,0]
	s_branch .Lhn_comp_b
.Lhn_nomod_b:
	global_load_dwordx4 v[0:3], v160, s[14:15] offset:-4096
	global_load_dwordx4 v[4:7], v160, s[14:15] offset:-3072
	global_load_dwordx4 v[8:11], v160, s[14:15] offset:-2048
	global_load_dwordx4 v[12:15], v160, s[14:15] offset:-1024
	global_load_dwordx4 v[16:19], v160, s[14:15] offset:0
	global_load_dwordx4 v[20:23], v160, s[14:15] offset:1024
	global_load_dwordx4 v[24:27], v160, s[14:15] offset:2048
	global_load_dwordx4 v[28:31], v160, s[14:15] offset:3072
	s_waitcnt vmcnt(16)
	v_pk_mul_f32 v[168:169], v[32:33], v[32:33]
	v_pk_mul_f32 v[170:171], v[34:35], v[34:35]
	v_pk_fma_f32 v[168:169], v[36:37], v[36:37], v[168:169]
	v_pk_fma_f32 v[170:171], v[38:39], v[38:39], v[170:171]
	v_pk_fma_f32 v[168:169], v[40:41], v[40:41], v[168:169]
	v_pk_fma_f32 v[170:171], v[42:43], v[42:43], v[170:171]
	v_pk_fma_f32 v[168:169], v[44:45], v[44:45], v[168:169]
	v_pk_fma_f32 v[170:171], v[46:47], v[46:47], v[170:171]
	v_pk_fma_f32 v[168:169], v[48:49], v[48:49], v[168:169]
	v_pk_fma_f32 v[170:171], v[50:51], v[50:51], v[170:171]
	v_pk_fma_f32 v[168:169], v[52:53], v[52:53], v[168:169]
	v_pk_fma_f32 v[170:171], v[54:55], v[54:55], v[170:171]
	v_pk_fma_f32 v[168:169], v[56:57], v[56:57], v[168:169]
	v_pk_fma_f32 v[170:171], v[58:59], v[58:59], v[170:171]
	v_pk_fma_f32 v[168:169], v[60:61], v[60:61], v[168:169]
	v_pk_fma_f32 v[170:171], v[62:63], v[62:63], v[170:171]
	s_nop 0
	v_pk_add_f32 v[168:169], v[168:169], v[170:171]
	s_nop 0
	v_add_f32_e32 v168, v168, v169
	ds_bpermute_b32 v169, v162, v168
	s_waitcnt lgkmcnt(0)
	v_add_f32_e32 v168, v168, v169
	ds_bpermute_b32 v169, v163, v168
	s_waitcnt lgkmcnt(0)
	v_add_f32_e32 v168, v168, v169
	ds_bpermute_b32 v169, v164, v168
	s_waitcnt lgkmcnt(0)
	v_add_f32_e32 v168, v168, v169
	ds_bpermute_b32 v169, v165, v168
	s_waitcnt lgkmcnt(0)
	v_add_f32_e32 v168, v168, v169
	ds_bpermute_b32 v169, v166, v168
	s_waitcnt lgkmcnt(0)
	v_add_f32_e32 v168, v168, v169
	ds_bpermute_b32 v169, v167, v168
	s_waitcnt lgkmcnt(0)
	v_add_f32_e32 v168, v168, v169
	v_mov_b32_e32 v169, 0x358637bd
	v_fmamk_f32 v168, v168, 0x3a000000, v169
	v_cmp_gt_f32_e32 vcc, 0xf800000, v168
	v_mul_f32_e32 v169, 0x4f800000, v168
	s_nop 0
	v_cndmask_b32_e32 v168, v168, v169, vcc
	v_sqrt_f32_e32 v169, v168
	s_nop 0
	v_add_u32_e32 v170, -1, v169
	v_fma_f32 v171, -v170, v169, v168
	v_cmp_ge_f32_e64 s[100:101], 0, v171
	v_add_u32_e32 v171, 1, v169
	s_nop 0
	v_cndmask_b32_e64 v170, v169, v170, s[100:101]
	v_fma_f32 v169, -v171, v169, v168
	v_cmp_lt_f32_e64 s[100:101], 0, v169
	s_nop 1
	v_cndmask_b32_e64 v169, v170, v171, s[100:101]
	v_mul_f32_e32 v170, 0x37800000, v169
	v_cndmask_b32_e32 v169, v169, v170, vcc
	v_mov_b32_e32 v170, 0x260
	v_cmp_class_f32_e32 vcc, v168, v170
	s_nop 1
	v_cndmask_b32_e32 v168, v169, v168, vcc
	v_div_scale_f32 v169, s[100:101], v168, v168, 1.0
	v_rcp_f32_e32 v170, v169
	s_nop 0
	v_fma_f32 v171, -v169, v170, 1.0
	v_fmac_f32_e32 v170, v171, v170
	v_div_scale_f32 v171, vcc, 1.0, v168, 1.0
	v_mul_f32_e32 v172, v171, v170
	v_fma_f32 v173, -v169, v172, v171
	v_fmac_f32_e32 v172, v173, v170
	v_fma_f32 v169, -v169, v172, v171
	s_nop 0
	v_div_fmas_f32 v169, v169, v170, v172
	v_div_fixup_f32 v172, v169, v168, 1.0
; __device__ __forceinline__ unsigned xb_add(unsigned* p, unsigned v) { return __hip_atomic_fetch_add(p, v, __ATOMIC_RELAXED, __HIP_MEMORY_SCOPE_AGENT); }
; __device__ __forceinline__ void phase_norm(PP p, int l, const float* mod, int lane, int wave) {
;     ...
;         for (int j = 0; j < 8; ++j) { const int col = 4 * lane + 256 * j;
;             const f32x4 g4 = *(const f32x4*)(ng + col), sh = *(const f32x4*)(modl + (size_t)b * NMOD + col), sc = *(const f32x4*)(modl + (size_t)b * NMOD + DM + col);
;             const f32x4 y = v[j] * rstd * g4 * (sc + 1.f) + sh;
;             u32x2 w; w.x = cvtpk(y.x, y.y); w.y = cvtpk(y.z, y.w); o8[64 * j] = w; }
; __device__ __forceinline__ void xcd_barrier(const XcdBarrier& b, const int tid) {
;     asm volatile("s_waitcnt vmcnt(0)" ::: "memory");
;     __syncthreads();
;     if (tid == 0) {
;         unsigned* bar = b.bar;
;         __builtin_amdgcn_s_waitcnt(0);
;         unsigned nloc = b.st[0], nx = b.st[1];
;         if (nloc == 0u) { xcd_barrier_complete(bar, b.x, nloc, nx); b.st[0] = nloc; b.st[1] = nx; }
;         const unsigned old = xb_add(&bar[XB_XSUB(b.x)], 1u);
.Lhn_comp_b:
	s_lshl_b32 s101, s4, 12
	s_add_u32 s12, s8, s101
	s_addc_u32 s13, s9, 0
	v_pk_mul_f32 v[32:33], v[32:33], v[172:173] op_sel_hi:[1,0]
	v_pk_mul_f32 v[34:35], v[34:35], v[172:173] op_sel_hi:[1,0]
	v_pk_mul_f32 v[32:33], v[64:65], v[32:33]
	v_pk_mul_f32 v[34:35], v[66:67], v[34:35]
	v_pk_fma_f32 v[32:33], v[96:97], v[32:33], v[128:129]
	v_pk_fma_f32 v[34:35], v[98:99], v[34:35], v[130:131]
	s_nop 0
	v_cvt_pk_bf16_f32 v32, v32, v33
	v_cvt_pk_bf16_f32 v33, v34, v35
	global_store_dwordx2 v161, v[32:33], s[12:13] offset:0
	v_pk_mul_f32 v[36:37], v[36:37], v[172:173] op_sel_hi:[1,0]
	v_pk_mul_f32 v[38:39], v[38:39], v[172:173] op_sel_hi:[1,0]
	v_pk_mul_f32 v[36:37], v[68:69], v[36:37]
	v_pk_mul_f32 v[38:39], v[70:71], v[38:39]
	v_pk_fma_f32 v[36:37], v[100:101], v[36:37], v[132:133]
	v_pk_fma_f32 v[38:39], v[102:103], v[38:39], v[134:135]
	s_nop 0
	v_cvt_pk_bf16_f32 v36, v36, v37
	v_cvt_pk_bf16_f32 v37, v38, v39
	global_store_dwordx2 v161, v[36:37], s[12:13] offset:512
	v_pk_mul_f32 v[40:41], v[40:41], v[172:173] op_sel_hi:[1,0]
	v_pk_mul_f32 v[42:43], v[42:43], v[172:173] op_sel_hi:[1,0]
	v_pk_mul_f32 v[40:41], v[72:73], v[40:41]
	v_pk_mul_f32 v[42:43], v[74:75], v[42:43]
	v_pk_fma_f32 v[40:41], v[104:105], v[40:41], v[136:137]
	v_pk_fma_f32 v[42:43], v[106:107], v[42:43], v[138:139]
	s_nop 0
	v_cvt_pk_bf16_f32 v40, v40, v41
	v_cvt_pk_bf16_f32 v41, v42, v43
	global_store_dwordx2 v161, v[40:41], s[12:13] offset:1024
	v_pk_mul_f32 v[44:45], v[44:45], v[172:173] op_sel_hi:[1,0]
	v_pk_mul_f32 v[46:47], v[46:47], v[172:173] op_sel_hi:[1,0]
	v_pk_mul_f32 v[44:45], v[76:77], v[44:45]
	v_pk_mul_f32 v[46:47], v[78:79], v[46:47]
	v_pk_fma_f32 v[44:45], v[108:109], v[44:45], v[140:141]
	v_pk_fma_f32 v[46:47], v[110:111], v[46:47], v[142:143]
	s_nop 0
	v_cvt_pk_bf16_f32 v44, v44, v45
	v_cvt_pk_bf16_f32 v45, v46, v47
	global_store_dwordx2 v161, v[44:45], s[12:13] offset:1536
	v_pk_mul_f32 v[48:49], v[48:49], v[172:173] op_sel_hi:[1,0]
	v_pk_mul_f32 v[50:51], v[50:51], v[172:173] op_sel_hi:[1,0]
	v_pk_mul_f32 v[48:49], v[80:81], v[48:49]
	v_pk_mul_f32 v[50:51], v[82:83], v[50:51]
	v_pk_fma_f32 v[48:49], v[112:113], v[48:49], v[144:145]
	v_pk_fma_f32 v[50:51], v[114:115], v[50:51], v[146:147]
	s_nop 0
	v_cvt_pk_bf16_f32 v48, v48, v49
	v_cvt_pk_bf16_f32 v49, v50, v51
	global_store_dwordx2 v161, v[48:49], s[12:13] offset:2048
	v_pk_mul_f32 v[52:53], v[52:53], v[172:173] op_sel_hi:[1,0]
	v_pk_mul_f32 v[54:55], v[54:55], v[172:173] op_sel_hi:[1,0]
	v_pk_mul_f32 v[52:53], v[84:85], v[52:53]
	v_pk_mul_f32 v[54:55], v[86:87], v[54:55]
	v_pk_fma_f32 v[52:53], v[116:117], v[52:53], v[148:149]
	v_pk_fma_f32 v[54:55], v[118:119], v[54:55], v[150:151]
	s_nop 0
	v_cvt_pk_bf16_f32 v52, v52, v53
	v_cvt_pk_bf16_f32 v53, v54, v55
	global_store_dwordx2 v161, v[52:53], s[12:13] offset:2560
	v_pk_mul_f32 v[56:57], v[56:57], v[172:173] op_sel_hi:[1,0]
	v_pk_mul_f32 v[58:59], v[58:59], v[172:173] op_sel_hi:[1,0]
	v_pk_mul_f32 v[56:57], v[88:89], v[56:57]
	v_pk_mul_f32 v[58:59], v[90:91], v[58:59]
	v_pk_fma_f32 v[56:57], v[120:121], v[56:57], v[152:153]
	v_pk_fma_f32 v[58:59], v[122:123], v[58:59], v[154:155]
	s_nop 0
	v_cvt_pk_bf16_f32 v56, v56, v57
	v_cvt_pk_bf16_f32 v57, v58, v59
	global_store_dwordx2 v161, v[56:57], s[12:13] offset:3072
	v_pk_mul_f32 v[60:61], v[60:61], v[172:173] op_sel_hi:[1,0]
	v_pk_mul_f32 v[62:63], v[62:63], v[172:173] op_sel_hi:[1,0]
	v_pk_mul_f32 v[60:61], v[92:93], v[60:61]
	v_pk_mul_f32 v[62:63], v[94:95], v[62:63]
	v_pk_fma_f32 v[60:61], v[124:125], v[60:61], v[156:157]
	v_pk_fma_f32 v[62:63], v[126:127], v[62:63], v[158:159]
	s_nop 0
	v_cvt_pk_bf16_f32 v60, v60, v61
	v_cvt_pk_bf16_f32 v61, v62, v63
	global_store_dwordx2 v161, v[60:61], s[12:13] offset:3584
	s_mov_b32 s4, s5
	s_cmp_lt_i32 s4, 0x4000
	s_cbranch_scc1 .Lhn_it_a
.Lhn_done:
.LBB0_138:
	s_mov_b64 s[4:5], s[68:69]
	s_mov_b32 s2, s80
	s_mov_b32 s3, s77
	s_getreg_b32 s6, hwreg(HW_REG_XCC_ID, 0, 4)
	s_waitcnt vmcnt(0)
	s_lshl_b32 s2, s2, 6
	v_mbcnt_lo_u32_b32 v0, -1, s3
	v_mbcnt_hi_u32_b32 v0, -1, v0
	v_sub_u32_e32 v0, 0, v0
	v_cmp_eq_u32_e32 vcc, s2, v0
	s_barrier
	s_and_saveexec_b64 s[2:3], vcc
	v_writelane_b32 v255, s16, 49
	s_cbranch_execz .LBB0_190
	s_add_i32 s48, 0, 0x24000
	v_mov_b32_e32 v0, s48
	s_load_dwordx2 s[4:5], s[4:5], 0x88
	s_waitcnt vmcnt(0) expcnt(0) lgkmcnt(0)
	ds_read_b32 v2, v0
	v_mov_b32_e32 v0, s92
	ds_read_b32 v0, v0
	s_and_b32 s33, s6, 15
	s_waitcnt lgkmcnt(1)
	v_cmp_ne_u32_e32 vcc, 0, v2
	s_cbranch_vccnz .LBB0_154
	s_add_u32 s6, s4, 0x80200
	s_addc_u32 s7, s5, 0
	s_add_u32 s8, s4, 0x80400
	s_addc_u32 s9, s5, 0
	s_add_u32 s10, s4, 0x80500
	s_addc_u32 s11, s5, 0
	s_add_u32 s12, s4, 0x80600
	s_addc_u32 s13, s5, 0
	s_add_u32 s14, s4, 0x80700
	s_addc_u32 s15, s5, 0
	s_add_u32 s16, s4, 0x80800
	s_addc_u32 s17, s5, 0
	s_add_u32 s18, s4, 0x80900
	s_addc_u32 s19, s5, 0
	s_add_u32 s20, s4, 0x80a00
	s_addc_u32 s21, s5, 0
	s_add_u32 s22, s4, 0x80b00
	s_addc_u32 s23, s5, 0
	s_add_u32 s24, s4, 0x80c00
	s_addc_u32 s25, s5, 0
	s_add_u32 s26, s4, 0x80d00
	s_addc_u32 s27, s5, 0
	s_add_u32 s28, s4, 0x80e00
	s_addc_u32 s29, s5, 0
	s_add_u32 s30, s4, 0x80f00
	s_addc_u32 s31, s5, 0
	s_add_u32 s34, s4, 0x81000
	s_addc_u32 s35, s5, 0
	s_add_u32 s36, s4, 0x81100
	s_addc_u32 s37, s5, 0
	s_add_u32 s38, s4, 0x81200
	s_addc_u32 s39, s5, 0
	s_add_u32 s40, s4, 0x81300
	s_addc_u32 s41, s5, 0
	s_mov_b32 s49, 1
	s_branch .LBB0_142

; __device__ __forceinline__ void phase_final(PP p, int lane, int wave) {
;     const int gw = blockIdx.x * 8 + wave, NGW = gridDim.x * 8;
;     for (int row = gw; row < MTOK; row += NGW) {
;         f32x4* xr = (f32x4*)(p->out + (size_t)row * DM) + lane;
;         f32x4 v[8]; float s = 0.f;
; #pragma unroll
;         for (int j = 0; j < 8; ++j) { v[j] = xr[64 * j]; s += (v[j].x * v[j].x + v[j].y * v[j].y) + (v[j].z * v[j].z + v[j].w * v[j].w); }
;         s = wave_sum(s);
;         const float rstd = 1.f / sqrtf(s * (1.f / DM) + RMS_EPS);
; #pragma unroll
;         for (int j = 0; j < 8; ++j) { const f32x4 g4 = *(const f32x4*)(p->final_g + 4 * lane + 256 * j); xr[64 * j] = v[j] * rstd * g4; }
.LBB0_658:
	s_add_i32 s2, s80, s81
	s_mov_b32 s0, 0
	s_cmpk_gt_i32 s2, 0x3fff
	s_cbranch_scc1 .LBB0_661
	s_mov_b32 s4, s2
	s_load_dwordx4 s[8:11], s[68:69], 0x78
	v_lshlrev_b32_e32 v160, 4, v239
	v_lshlrev_b32_e32 v161, 3, v239
	v_xor_b32_e32 v162, 1, v239
	v_xor_b32_e32 v163, 2, v239
	v_xor_b32_e32 v164, 4, v239
	v_xor_b32_e32 v165, 8, v239
	v_xor_b32_e32 v166, 16, v239
	v_xor_b32_e32 v167, 32, v239
	v_lshlrev_b32_e32 v162, 2, v162
	v_lshlrev_b32_e32 v163, 2, v163
	v_lshlrev_b32_e32 v164, 2, v164
	v_lshlrev_b32_e32 v165, 2, v165
	v_lshlrev_b32_e32 v166, 2, v166
	v_lshlrev_b32_e32 v167, 2, v167
	s_waitcnt lgkmcnt(0)
	s_add_u32 s2, s10, 0x1000
	s_addc_u32 s3, s11, 0
	s_add_u32 s12, s8, 0x1000
	s_addc_u32 s13, s9, 0
	s_lshl_b32 s5, s4, 13
	s_add_u32 s14, s2, s5
	s_addc_u32 s15, s3, 0
	global_load_dwordx4 v[64:67], v160, s[12:13] offset:-4096
	global_load_dwordx4 v[68:71], v160, s[12:13] offset:-3072
	global_load_dwordx4 v[72:75], v160, s[12:13] offset:-2048
	global_load_dwordx4 v[76:79], v160, s[12:13] offset:-1024
	global_load_dwordx4 v[80:83], v160, s[12:13] offset:0
	global_load_dwordx4 v[84:87], v160, s[12:13] offset:1024
	global_load_dwordx4 v[88:91], v160, s[12:13] offset:2048
	global_load_dwordx4 v[92:95], v160, s[12:13] offset:3072
	global_load_dwordx4 v[0:3], v160, s[14:15] offset:-4096
	global_load_dwordx4 v[4:7], v160, s[14:15] offset:-3072
	global_load_dwordx4 v[8:11], v160, s[14:15] offset:-2048
	global_load_dwordx4 v[12:15], v160, s[14:15] offset:-1024
	global_load_dwordx4 v[16:19], v160, s[14:15] offset:0
	global_load_dwordx4 v[20:23], v160, s[14:15] offset:1024
	global_load_dwordx4 v[24:27], v160, s[14:15] offset:2048
	global_load_dwordx4 v[28:31], v160, s[14:15] offset:3072
.Lhf_it_f:
	s_add_i32 s5, s4, s74
	s_cmp_lt_i32 s5, 0x4000
	s_cselect_b32 s99, s5, s4
	s_lshl_b32 s99, s99, 13
	s_add_u32 s14, s2, s99
	s_addc_u32 s15, s3, 0
	global_load_dwordx4 v[32:35], v160, s[14:15] offset:-4096
	global_load_dwordx4 v[36:39], v160, s[14:15] offset:-3072
	global_load_dwordx4 v[40:43], v160, s[14:15] offset:-2048
	global_load_dwordx4 v[44:47], v160, s[14:15] offset:-1024
	global_load_dwordx4 v[48:51], v160, s[14:15] offset:0
	global_load_dwordx4 v[52:55], v160, s[14:15] offset:1024
	global_load_dwordx4 v[56:59], v160, s[14:15] offset:2048
	global_load_dwordx4 v[60:63], v160, s[14:15] offset:3072
	s_waitcnt vmcnt(8)
	v_pk_mul_f32 v[168:169], v[0:1], v[0:1]
	v_pk_mul_f32 v[170:171], v[2:3], v[2:3]
	v_pk_fma_f32 v[168:169], v[4:5], v[4:5], v[168:169]
	v_pk_fma_f32 v[170:171], v[6:7], v[6:7], v[170:171]
	v_pk_fma_f32 v[168:169], v[8:9], v[8:9], v[168:169]
	v_pk_fma_f32 v[170:171], v[10:11], v[10:11], v[170:171]
	v_pk_fma_f32 v[168:169], v[12:13], v[12:13], v[168:169]
	v_pk_fma_f32 v[170:171], v[14:15], v[14:15], v[170:171]
	v_pk_fma_f32 v[168:169], v[16:17], v[16:17], v[168:169]
	v_pk_fma_f32 v[170:171], v[18:19], v[18:19], v[170:171]
	v_pk_fma_f32 v[168:169], v[20:21], v[20:21], v[168:169]
	v_pk_fma_f32 v[170:171], v[22:23], v[22:23], v[170:171]
	v_pk_fma_f32 v[168:169], v[24:25], v[24:25], v[168:169]
	v_pk_fma_f32 v[170:171], v[26:27], v[26:27], v[170:171]
	v_pk_fma_f32 v[168:169], v[28:29], v[28:29], v[168:169]
	v_pk_fma_f32 v[170:171], v[30:31], v[30:31], v[170:171]
	s_nop 0
	v_pk_add_f32 v[168:169], v[168:169], v[170:171]
	s_nop 0
	v_add_f32_e32 v168, v168, v169
	ds_bpermute_b32 v169, v162, v168
	s_waitcnt lgkmcnt(0)
	v_add_f32_e32 v168, v168, v169
	ds_bpermute_b32 v169, v163, v168
	s_waitcnt lgkmcnt(0)
	v_add_f32_e32 v168, v168, v169
	ds_bpermute_b32 v169, v164, v168
	s_waitcnt lgkmcnt(0)
	v_add_f32_e32 v168, v168, v169
	ds_bpermute_b32 v169, v165, v168
	s_waitcnt lgkmcnt(0)
	v_add_f32_e32 v168, v168, v169
	ds_bpermute_b32 v169, v166, v168
	s_waitcnt lgkmcnt(0)
	v_add_f32_e32 v168, v168, v169
	ds_bpermute_b32 v169, v167, v168
	s_waitcnt lgkmcnt(0)
	v_add_f32_e32 v168, v168, v169
	v_mov_b32_e32 v169, 0x358637bd
	v_fmamk_f32 v168, v168, 0x3a000000, v169
	v_cmp_gt_f32_e32 vcc, 0xf800000, v168
	v_mul_f32_e32 v169, 0x4f800000, v168
	s_nop 0
	v_cndmask_b32_e32 v168, v168, v169, vcc
	v_sqrt_f32_e32 v169, v168
	s_nop 0
	v_add_u32_e32 v170, -1, v169
	v_fma_f32 v171, -v170, v169, v168
	v_cmp_ge_f32_e64 s[100:101], 0, v171
	v_add_u32_e32 v171, 1, v169
	s_nop 0
	v_cndmask_b32_e64 v170, v169, v170, s[100:101]
	v_fma_f32 v169, -v171, v169, v168
	v_cmp_lt_f32_e64 s[100:101], 0, v169
	s_nop 1
	v_cndmask_b32_e64 v169, v170, v171, s[100:101]
	v_mul_f32_e32 v170, 0x37800000, v169
	v_cndmask_b32_e32 v169, v169, v170, vcc
	v_mov_b32_e32 v170, 0x260
	v_cmp_class_f32_e32 vcc, v168, v170
	s_nop 1
	v_cndmask_b32_e32 v168, v169, v168, vcc
	v_div_scale_f32 v169, s[100:101], v168, v168, 1.0
	v_rcp_f32_e32 v170, v169
	s_nop 0
	v_fma_f32 v171, -v169, v170, 1.0
	v_fmac_f32_e32 v170, v171, v170
	v_div_scale_f32 v171, vcc, 1.0, v168, 1.0
	v_mul_f32_e32 v172, v171, v170
	v_fma_f32 v173, -v169, v172, v171
	v_fmac_f32_e32 v172, v173, v170
	v_fma_f32 v169, -v169, v172, v171
	s_nop 0
	v_div_fmas_f32 v169, v169, v170, v172
	v_div_fixup_f32 v172, v169, v168, 1.0
	s_lshl_b32 s101, s4, 13
	s_add_u32 s12, s2, s101
	s_addc_u32 s13, s3, 0
	v_pk_mul_f32 v[0:1], v[0:1], v[172:173] op_sel_hi:[1,0]
	v_pk_mul_f32 v[2:3], v[2:3], v[172:173] op_sel_hi:[1,0]
	v_pk_mul_f32 v[0:1], v[64:65], v[0:1]
	v_pk_mul_f32 v[2:3], v[66:67], v[2:3]
	global_store_dwordx4 v160, v[0:3], s[12:13] offset:-4096
	v_pk_mul_f32 v[4:5], v[4:5], v[172:173] op_sel_hi:[1,0]
	v_pk_mul_f32 v[6:7], v[6:7], v[172:173] op_sel_hi:[1,0]
	v_pk_mul_f32 v[4:5], v[68:69], v[4:5]
	v_pk_mul_f32 v[6:7], v[70:71], v[6:7]
	global_store_dwordx4 v160, v[4:7], s[12:13] offset:-3072
	v_pk_mul_f32 v[8:9], v[8:9], v[172:173] op_sel_hi:[1,0]
; __device__ __forceinline__ void phase_final(PP p, int lane, int wave) {
;     ...
;         for (int j = 0; j < 8; ++j) { v[j] = xr[64 * j]; s += (v[j].x * v[j].x + v[j].y * v[j].y) + (v[j].z * v[j].z + v[j].w * v[j].w); }
;         s = wave_sum(s);
;         const float rstd = 1.f / sqrtf(s * (1.f / DM) + RMS_EPS);
; #pragma unroll
;         for (int j = 0; j < 8; ++j) { const f32x4 g4 = *(const f32x4*)(p->final_g + 4 * lane + 256 * j); xr[64 * j] = v[j] * rstd * g4; }
	v_pk_mul_f32 v[10:11], v[10:11], v[172:173] op_sel_hi:[1,0]
	v_pk_mul_f32 v[8:9], v[72:73], v[8:9]
	v_pk_mul_f32 v[10:11], v[74:75], v[10:11]
	global_store_dwordx4 v160, v[8:11], s[12:13] offset:-2048
	v_pk_mul_f32 v[12:13], v[12:13], v[172:173] op_sel_hi:[1,0]
	v_pk_mul_f32 v[14:15], v[14:15], v[172:173] op_sel_hi:[1,0]
	v_pk_mul_f32 v[12:13], v[76:77], v[12:13]
	v_pk_mul_f32 v[14:15], v[78:79], v[14:15]
	global_store_dwordx4 v160, v[12:15], s[12:13] offset:-1024
	v_pk_mul_f32 v[16:17], v[16:17], v[172:173] op_sel_hi:[1,0]
	v_pk_mul_f32 v[18:19], v[18:19], v[172:173] op_sel_hi:[1,0]
	v_pk_mul_f32 v[16:17], v[80:81], v[16:17]
	v_pk_mul_f32 v[18:19], v[82:83], v[18:19]
	global_store_dwordx4 v160, v[16:19], s[12:13] offset:0
	v_pk_mul_f32 v[20:21], v[20:21], v[172:173] op_sel_hi:[1,0]
	v_pk_mul_f32 v[22:23], v[22:23], v[172:173] op_sel_hi:[1,0]
	v_pk_mul_f32 v[20:21], v[84:85], v[20:21]
	v_pk_mul_f32 v[22:23], v[86:87], v[22:23]
	global_store_dwordx4 v160, v[20:23], s[12:13] offset:1024
	v_pk_mul_f32 v[24:25], v[24:25], v[172:173] op_sel_hi:[1,0]
	v_pk_mul_f32 v[26:27], v[26:27], v[172:173] op_sel_hi:[1,0]
	v_pk_mul_f32 v[24:25], v[88:89], v[24:25]
	v_pk_mul_f32 v[26:27], v[90:91], v[26:27]
	global_store_dwordx4 v160, v[24:27], s[12:13] offset:2048
	v_pk_mul_f32 v[28:29], v[28:29], v[172:173] op_sel_hi:[1,0]
	v_pk_mul_f32 v[30:31], v[30:31], v[172:173] op_sel_hi:[1,0]
	v_pk_mul_f32 v[28:29], v[92:93], v[28:29]
	v_pk_mul_f32 v[30:31], v[94:95], v[30:31]
	global_store_dwordx4 v160, v[28:31], s[12:13] offset:3072
	s_mov_b32 s4, s5
	s_cmp_lt_i32 s4, 0x4000
	s_cbranch_scc0 .Lhf_done
.Lhf_it_b:
	s_add_i32 s5, s4, s74
	s_cmp_lt_i32 s5, 0x4000
	s_cselect_b32 s99, s5, s4
	s_lshl_b32 s99, s99, 13
	s_add_u32 s14, s2, s99
	s_addc_u32 s15, s3, 0
	global_load_dwordx4 v[0:3], v160, s[14:15] offset:-4096
	global_load_dwordx4 v[4:7], v160, s[14:15] offset:-3072
	global_load_dwordx4 v[8:11], v160, s[14:15] offset:-2048
	global_load_dwordx4 v[12:15], v160, s[14:15] offset:-1024
	global_load_dwordx4 v[16:19], v160, s[14:15] offset:0
	global_load_dwordx4 v[20:23], v160, s[14:15] offset:1024
	global_load_dwordx4 v[24:27], v160, s[14:15] offset:2048
	global_load_dwordx4 v[28:31], v160, s[14:15] offset:3072
	s_waitcnt vmcnt(16)
	v_pk_mul_f32 v[168:169], v[32:33], v[32:33]
	v_pk_mul_f32 v[170:171], v[34:35], v[34:35]
	v_pk_fma_f32 v[168:169], v[36:37], v[36:37], v[168:169]
	v_pk_fma_f32 v[170:171], v[38:39], v[38:39], v[170:171]
	v_pk_fma_f32 v[168:169], v[40:41], v[40:41], v[168:169]
	v_pk_fma_f32 v[170:171], v[42:43], v[42:43], v[170:171]
	v_pk_fma_f32 v[168:169], v[44:45], v[44:45], v[168:169]
	v_pk_fma_f32 v[170:171], v[46:47], v[46:47], v[170:171]
	v_pk_fma_f32 v[168:169], v[48:49], v[48:49], v[168:169]
	v_pk_fma_f32 v[170:171], v[50:51], v[50:51], v[170:171]
	v_pk_fma_f32 v[168:169], v[52:53], v[52:53], v[168:169]
	v_pk_fma_f32 v[170:171], v[54:55], v[54:55], v[170:171]
	v_pk_fma_f32 v[168:169], v[56:57], v[56:57], v[168:169]
	v_pk_fma_f32 v[170:171], v[58:59], v[58:59], v[170:171]
	v_pk_fma_f32 v[168:169], v[60:61], v[60:61], v[168:169]
	v_pk_fma_f32 v[170:171], v[62:63], v[62:63], v[170:171]
	s_nop 0
	v_pk_add_f32 v[168:169], v[168:169], v[170:171]
	s_nop 0
	v_add_f32_e32 v168, v168, v169
	ds_bpermute_b32 v169, v162, v168
	s_waitcnt lgkmcnt(0)
	v_add_f32_e32 v168, v168, v169
	ds_bpermute_b32 v169, v163, v168
	s_waitcnt lgkmcnt(0)
	v_add_f32_e32 v168, v168, v169
	ds_bpermute_b32 v169, v164, v168
	s_waitcnt lgkmcnt(0)
	v_add_f32_e32 v168, v168, v169
	ds_bpermute_b32 v169, v165, v168
	s_waitcnt lgkmcnt(0)
	v_add_f32_e32 v168, v168, v169
	ds_bpermute_b32 v169, v166, v168
	s_waitcnt lgkmcnt(0)
	v_add_f32_e32 v168, v168, v169
	ds_bpermute_b32 v169, v167, v168
	s_waitcnt lgkmcnt(0)
	v_add_f32_e32 v168, v168, v169
	v_mov_b32_e32 v169, 0x358637bd
	v_fmamk_f32 v168, v168, 0x3a000000, v169
	v_cmp_gt_f32_e32 vcc, 0xf800000, v168
	v_mul_f32_e32 v169, 0x4f800000, v168
	s_nop 0
	v_cndmask_b32_e32 v168, v168, v169, vcc
	v_sqrt_f32_e32 v169, v168
	s_nop 0
	v_add_u32_e32 v170, -1, v169
	v_fma_f32 v171, -v170, v169, v168
	v_cmp_ge_f32_e64 s[100:101], 0, v171
	v_add_u32_e32 v171, 1, v169
	s_nop 0
	v_cndmask_b32_e64 v170, v169, v170, s[100:101]
	v_fma_f32 v169, -v171, v169, v168
	v_cmp_lt_f32_e64 s[100:101], 0, v169
	s_nop 1
	v_cndmask_b32_e64 v169, v170, v171, s[100:101]
	v_mul_f32_e32 v170, 0x37800000, v169
	v_cndmask_b32_e32 v169, v169, v170, vcc
	v_mov_b32_e32 v170, 0x260
	v_cmp_class_f32_e32 vcc, v168, v170
	s_nop 1
	v_cndmask_b32_e32 v168, v169, v168, vcc
	v_div_scale_f32 v169, s[100:101], v168, v168, 1.0
	v_rcp_f32_e32 v170, v169
	s_nop 0
	v_fma_f32 v171, -v169, v170, 1.0
	v_fmac_f32_e32 v170, v171, v170
	v_div_scale_f32 v171, vcc, 1.0, v168, 1.0
	v_mul_f32_e32 v172, v171, v170
	v_fma_f32 v173, -v169, v172, v171
	v_fmac_f32_e32 v172, v173, v170
	v_fma_f32 v169, -v169, v172, v171
	s_nop 0
	v_div_fmas_f32 v169, v169, v170, v172
	v_div_fixup_f32 v172, v169, v168, 1.0
	s_lshl_b32 s101, s4, 13
	s_add_u32 s12, s2, s101
	s_addc_u32 s13, s3, 0
	v_pk_mul_f32 v[32:33], v[32:33], v[172:173] op_sel_hi:[1,0]
	v_pk_mul_f32 v[34:35], v[34:35], v[172:173] op_sel_hi:[1,0]
	v_pk_mul_f32 v[32:33], v[64:65], v[32:33]
	v_pk_mul_f32 v[34:35], v[66:67], v[34:35]
	global_store_dwordx4 v160, v[32:35], s[12:13] offset:-4096
	v_pk_mul_f32 v[36:37], v[36:37], v[172:173] op_sel_hi:[1,0]
	v_pk_mul_f32 v[38:39], v[38:39], v[172:173] op_sel_hi:[1,0]
	v_pk_mul_f32 v[36:37], v[68:69], v[36:37]
	v_pk_mul_f32 v[38:39], v[70:71], v[38:39]
	global_store_dwordx4 v160, v[36:39], s[12:13] offset:-3072
	v_pk_mul_f32 v[40:41], v[40:41], v[172:173] op_sel_hi:[1,0]
	v_pk_mul_f32 v[42:43], v[42:43], v[172:173] op_sel_hi:[1,0]
; __device__ __forceinline__ void phase_final(PP p, int lane, int wave) {
;     ...
;         for (int j = 0; j < 8; ++j) { const f32x4 g4 = *(const f32x4*)(p->final_g + 4 * lane + 256 * j); xr[64 * j] = v[j] * rstd * g4; }
	v_pk_mul_f32 v[40:41], v[72:73], v[40:41]
	v_pk_mul_f32 v[42:43], v[74:75], v[42:43]
	global_store_dwordx4 v160, v[40:43], s[12:13] offset:-2048
	v_pk_mul_f32 v[44:45], v[44:45], v[172:173] op_sel_hi:[1,0]
	v_pk_mul_f32 v[46:47], v[46:47], v[172:173] op_sel_hi:[1,0]
	v_pk_mul_f32 v[44:45], v[76:77], v[44:45]
	v_pk_mul_f32 v[46:47], v[78:79], v[46:47]
	global_store_dwordx4 v160, v[44:47], s[12:13] offset:-1024
	v_pk_mul_f32 v[48:49], v[48:49], v[172:173] op_sel_hi:[1,0]
	v_pk_mul_f32 v[50:51], v[50:51], v[172:173] op_sel_hi:[1,0]
	v_pk_mul_f32 v[48:49], v[80:81], v[48:49]
	v_pk_mul_f32 v[50:51], v[82:83], v[50:51]
	global_store_dwordx4 v160, v[48:51], s[12:13] offset:0
	v_pk_mul_f32 v[52:53], v[52:53], v[172:173] op_sel_hi:[1,0]
	v_pk_mul_f32 v[54:55], v[54:55], v[172:173] op_sel_hi:[1,0]
	v_pk_mul_f32 v[52:53], v[84:85], v[52:53]
	v_pk_mul_f32 v[54:55], v[86:87], v[54:55]
	global_store_dwordx4 v160, v[52:55], s[12:13] offset:1024
	v_pk_mul_f32 v[56:57], v[56:57], v[172:173] op_sel_hi:[1,0]
	v_pk_mul_f32 v[58:59], v[58:59], v[172:173] op_sel_hi:[1,0]
	v_pk_mul_f32 v[56:57], v[88:89], v[56:57]
	v_pk_mul_f32 v[58:59], v[90:91], v[58:59]
	global_store_dwordx4 v160, v[56:59], s[12:13] offset:2048
	v_pk_mul_f32 v[60:61], v[60:61], v[172:173] op_sel_hi:[1,0]
	v_pk_mul_f32 v[62:63], v[62:63], v[172:173] op_sel_hi:[1,0]
	v_pk_mul_f32 v[60:61], v[92:93], v[60:61]
	v_pk_mul_f32 v[62:63], v[94:95], v[62:63]
	global_store_dwordx4 v160, v[60:63], s[12:13] offset:3072
	s_mov_b32 s4, s5
	s_cmp_lt_i32 s4, 0x4000
	s_cbranch_scc0 .Lhf_done
; __device__ __forceinline__ void phase_final(PP p, int lane, int wave) {
;     ...
;     for (int row = gw; row < MTOK; row += NGW) {
;         f32x4* xr = (f32x4*)(p->out + (size_t)row * DM) + lane;
;         f32x4 v[8]; float s = 0.f;
; #pragma unroll
;         for (int j = 0; j < 8; ++j) { v[j] = xr[64 * j]; s += (v[j].x * v[j].x + v[j].y * v[j].y) + (v[j].z * v[j].z + v[j].w * v[j].w); }
;         s = wave_sum(s);
;         const float rstd = 1.f / sqrtf(s * (1.f / DM) + RMS_EPS);
; #pragma unroll
;         for (int j = 0; j < 8; ++j) { const f32x4 g4 = *(const f32x4*)(p->final_g + 4 * lane + 256 * j); xr[64 * j] = v[j] * rstd * g4; }
.Lhf_it_a:
	s_add_i32 s5, s4, s74
	s_cmp_lt_i32 s5, 0x4000
	s_cselect_b32 s99, s5, s4
	s_lshl_b32 s99, s99, 13
	s_add_u32 s14, s2, s99
	s_addc_u32 s15, s3, 0
	global_load_dwordx4 v[32:35], v160, s[14:15] offset:-4096
	global_load_dwordx4 v[36:39], v160, s[14:15] offset:-3072
	global_load_dwordx4 v[40:43], v160, s[14:15] offset:-2048
	global_load_dwordx4 v[44:47], v160, s[14:15] offset:-1024
	global_load_dwordx4 v[48:51], v160, s[14:15] offset:0
	global_load_dwordx4 v[52:55], v160, s[14:15] offset:1024
	global_load_dwordx4 v[56:59], v160, s[14:15] offset:2048
	global_load_dwordx4 v[60:63], v160, s[14:15] offset:3072
	s_waitcnt vmcnt(16)
	v_pk_mul_f32 v[168:169], v[0:1], v[0:1]
	v_pk_mul_f32 v[170:171], v[2:3], v[2:3]
	v_pk_fma_f32 v[168:169], v[4:5], v[4:5], v[168:169]
	v_pk_fma_f32 v[170:171], v[6:7], v[6:7], v[170:171]
	v_pk_fma_f32 v[168:169], v[8:9], v[8:9], v[168:169]
	v_pk_fma_f32 v[170:171], v[10:11], v[10:11], v[170:171]
	v_pk_fma_f32 v[168:169], v[12:13], v[12:13], v[168:169]
	v_pk_fma_f32 v[170:171], v[14:15], v[14:15], v[170:171]
	v_pk_fma_f32 v[168:169], v[16:17], v[16:17], v[168:169]
	v_pk_fma_f32 v[170:171], v[18:19], v[18:19], v[170:171]
	v_pk_fma_f32 v[168:169], v[20:21], v[20:21], v[168:169]
	v_pk_fma_f32 v[170:171], v[22:23], v[22:23], v[170:171]
	v_pk_fma_f32 v[168:169], v[24:25], v[24:25], v[168:169]
	v_pk_fma_f32 v[170:171], v[26:27], v[26:27], v[170:171]
	v_pk_fma_f32 v[168:169], v[28:29], v[28:29], v[168:169]
	v_pk_fma_f32 v[170:171], v[30:31], v[30:31], v[170:171]
	s_nop 0
	v_pk_add_f32 v[168:169], v[168:169], v[170:171]
	s_nop 0
	v_add_f32_e32 v168, v168, v169
	ds_bpermute_b32 v169, v162, v168
	s_waitcnt lgkmcnt(0)
	v_add_f32_e32 v168, v168, v169
	ds_bpermute_b32 v169, v163, v168
	s_waitcnt lgkmcnt(0)
	v_add_f32_e32 v168, v168, v169
	ds_bpermute_b32 v169, v164, v168
	s_waitcnt lgkmcnt(0)
	v_add_f32_e32 v168, v168, v169
	ds_bpermute_b32 v169, v165, v168
	s_waitcnt lgkmcnt(0)
	v_add_f32_e32 v168, v168, v169
	ds_bpermute_b32 v169, v166, v168
	s_waitcnt lgkmcnt(0)
	v_add_f32_e32 v168, v168, v169
	ds_bpermute_b32 v169, v167, v168
	s_waitcnt lgkmcnt(0)
	v_add_f32_e32 v168, v168, v169
	v_mov_b32_e32 v169, 0x358637bd
	v_fmamk_f32 v168, v168, 0x3a000000, v169
	v_cmp_gt_f32_e32 vcc, 0xf800000, v168
	v_mul_f32_e32 v169, 0x4f800000, v168
	s_nop 0
	v_cndmask_b32_e32 v168, v168, v169, vcc
	v_sqrt_f32_e32 v169, v168
	s_nop 0
	v_add_u32_e32 v170, -1, v169
	v_fma_f32 v171, -v170, v169, v168
	v_cmp_ge_f32_e64 s[100:101], 0, v171
	v_add_u32_e32 v171, 1, v169
	s_nop 0
	v_cndmask_b32_e64 v170, v169, v170, s[100:101]
	v_fma_f32 v169, -v171, v169, v168
	v_cmp_lt_f32_e64 s[100:101], 0, v169
	s_nop 1
	v_cndmask_b32_e64 v169, v170, v171, s[100:101]
	v_mul_f32_e32 v170, 0x37800000, v169
	v_cndmask_b32_e32 v169, v169, v170, vcc
	v_mov_b32_e32 v170, 0x260
	v_cmp_class_f32_e32 vcc, v168, v170
	s_nop 1
	v_cndmask_b32_e32 v168, v169, v168, vcc
	v_div_scale_f32 v169, s[100:101], v168, v168, 1.0
	v_rcp_f32_e32 v170, v169
	s_nop 0
	v_fma_f32 v171, -v169, v170, 1.0
	v_fmac_f32_e32 v170, v171, v170
	v_div_scale_f32 v171, vcc, 1.0, v168, 1.0
	v_mul_f32_e32 v172, v171, v170
	v_fma_f32 v173, -v169, v172, v171
	v_fmac_f32_e32 v172, v173, v170
	v_fma_f32 v169, -v169, v172, v171
	s_nop 0
	v_div_fmas_f32 v169, v169, v170, v172
	v_div_fixup_f32 v172, v169, v168, 1.0
	s_lshl_b32 s101, s4, 13
	s_add_u32 s12, s2, s101
	s_addc_u32 s13, s3, 0
	v_pk_mul_f32 v[0:1], v[0:1], v[172:173] op_sel_hi:[1,0]
	v_pk_mul_f32 v[2:3], v[2:3], v[172:173] op_sel_hi:[1,0]
	v_pk_mul_f32 v[0:1], v[64:65], v[0:1]
	v_pk_mul_f32 v[2:3], v[66:67], v[2:3]
	global_store_dwordx4 v160, v[0:3], s[12:13] offset:-4096
	v_pk_mul_f32 v[4:5], v[4:5], v[172:173] op_sel_hi:[1,0]
	v_pk_mul_f32 v[6:7], v[6:7], v[172:173] op_sel_hi:[1,0]
	v_pk_mul_f32 v[4:5], v[68:69], v[4:5]
	v_pk_mul_f32 v[6:7], v[70:71], v[6:7]
	global_store_dwordx4 v160, v[4:7], s[12:13] offset:-3072
	v_pk_mul_f32 v[8:9], v[8:9], v[172:173] op_sel_hi:[1,0]
	v_pk_mul_f32 v[10:11], v[10:11], v[172:173] op_sel_hi:[1,0]
	v_pk_mul_f32 v[8:9], v[72:73], v[8:9]
	v_pk_mul_f32 v[10:11], v[74:75], v[10:11]
	global_store_dwordx4 v160, v[8:11], s[12:13] offset:-2048
	v_pk_mul_f32 v[12:13], v[12:13], v[172:173] op_sel_hi:[1,0]
	v_pk_mul_f32 v[14:15], v[14:15], v[172:173] op_sel_hi:[1,0]
	v_pk_mul_f32 v[12:13], v[76:77], v[12:13]
	v_pk_mul_f32 v[14:15], v[78:79], v[14:15]
	global_store_dwordx4 v160, v[12:15], s[12:13] offset:-1024
	v_pk_mul_f32 v[16:17], v[16:17], v[172:173] op_sel_hi:[1,0]
	v_pk_mul_f32 v[18:19], v[18:19], v[172:173] op_sel_hi:[1,0]
	v_pk_mul_f32 v[16:17], v[80:81], v[16:17]
	v_pk_mul_f32 v[18:19], v[82:83], v[18:19]
	global_store_dwordx4 v160, v[16:19], s[12:13] offset:0
	v_pk_mul_f32 v[20:21], v[20:21], v[172:173] op_sel_hi:[1,0]
	v_pk_mul_f32 v[22:23], v[22:23], v[172:173] op_sel_hi:[1,0]
	v_pk_mul_f32 v[20:21], v[84:85], v[20:21]
	v_pk_mul_f32 v[22:23], v[86:87], v[22:23]
	global_store_dwordx4 v160, v[20:23], s[12:13] offset:1024
	v_pk_mul_f32 v[24:25], v[24:25], v[172:173] op_sel_hi:[1,0]
	v_pk_mul_f32 v[26:27], v[26:27], v[172:173] op_sel_hi:[1,0]
	v_pk_mul_f32 v[24:25], v[88:89], v[24:25]
	v_pk_mul_f32 v[26:27], v[90:91], v[26:27]
	global_store_dwordx4 v160, v[24:27], s[12:13] offset:2048
	v_pk_mul_f32 v[28:29], v[28:29], v[172:173] op_sel_hi:[1,0]
	v_pk_mul_f32 v[30:31], v[30:31], v[172:173] op_sel_hi:[1,0]
	v_pk_mul_f32 v[28:29], v[92:93], v[28:29]
	v_pk_mul_f32 v[30:31], v[94:95], v[30:31]
	global_store_dwordx4 v160, v[28:31], s[12:13] offset:3072
	s_mov_b32 s4, s5
	s_cmp_lt_i32 s4, 0x4000
	s_cbranch_scc1 .Lhf_it_b
.Lhf_done:
.LBB0_661:
	s_endpgm

; __global__ void __launch_bounds__(512, 2) fwd_megakernel(Params p_unused) {
	.amdhsa_kernel _Z14fwd_megakernel6Params
		.amdhsa_group_segment_fixed_size 0
		.amdhsa_private_segment_fixed_size 0
		.amdhsa_kernarg_size 400
		.amdhsa_user_sgpr_count 2
		.amdhsa_user_sgpr_dispatch_ptr 0
		.amdhsa_user_sgpr_queue_ptr 0
		.amdhsa_user_sgpr_kernarg_segment_ptr 1
		.amdhsa_user_sgpr_dispatch_id 0
		.amdhsa_user_sgpr_kernarg_preload_length 0
		.amdhsa_user_sgpr_kernarg_preload_offset 0
		.amdhsa_user_sgpr_private_segment_size 0
		.amdhsa_uses_dynamic_stack 0
		.amdhsa_enable_private_segment 0
		.amdhsa_system_sgpr_workgroup_id_x 1
		.amdhsa_system_sgpr_workgroup_id_y 0
		.amdhsa_system_sgpr_workgroup_id_z 0
		.amdhsa_system_sgpr_workgroup_info 0
		.amdhsa_system_vgpr_workitem_id 2
		.amdhsa_next_free_vgpr 256
		.amdhsa_next_free_sgpr 102
		.amdhsa_accum_offset 256
		.amdhsa_reserve_vcc 1
		.amdhsa_float_round_mode_32 0
		.amdhsa_float_round_mode_16_64 0
		.amdhsa_float_denorm_mode_32 3
		.amdhsa_float_denorm_mode_16_64 3
		.amdhsa_dx10_clamp 1
		.amdhsa_ieee_mode 1
		.amdhsa_fp16_overflow 0
		.amdhsa_tg_split 0
		.amdhsa_exception_fp_ieee_invalid_op 0
		.amdhsa_exception_fp_denorm_src 0
		.amdhsa_exception_fp_ieee_div_zero 0
		.amdhsa_exception_fp_ieee_overflow 0
		.amdhsa_exception_fp_ieee_underflow 0
		.amdhsa_exception_fp_ieee_inexact 0
		.amdhsa_exception_int_div_zero 0
	.end_amdhsa_kernel

; __global__ void __launch_bounds__(512, 2) fwd_megakernel(Params p_unused) {
.Lfunc_end0:
	.size	_Z14fwd_megakernel6Params, .Lfunc_end0-_Z14fwd_megakernel6Params
	.set _Z14fwd_megakernel6Params.num_vgpr, 256
	.set _Z14fwd_megakernel6Params.num_agpr, 0
	.set _Z14fwd_megakernel6Params.numbered_sgpr, 102
	.set _Z14fwd_megakernel6Params.num_named_barrier, 0
	.set _Z14fwd_megakernel6Params.private_seg_size, 0
	.set _Z14fwd_megakernel6Params.uses_vcc, 1
	.set _Z14fwd_megakernel6Params.uses_flat_scratch, 0
	.set _Z14fwd_megakernel6Params.has_dyn_sized_stack, 0
	.set _Z14fwd_megakernel6Params.has_recursion, 0
	.set _Z14fwd_megakernel6Params.has_indirect_call, 0

; __global__ void __launch_bounds__(512, 2) fwd_megakernel(Params p_unused) {
amdhsa.kernels:
  - .agpr_count:     0
    .args:
      - .offset:         0
        .size:           144
        .value_kind:     by_value
      - .offset:         144
        .size:           4
        .value_kind:     hidden_block_count_x
      - .offset:         148
        .size:           4
        .value_kind:     hidden_block_count_y
      - .offset:         152
        .size:           4
        .value_kind:     hidden_block_count_z
      - .offset:         156
        .size:           2
        .value_kind:     hidden_group_size_x
      - .offset:         158
        .size:           2
        .value_kind:     hidden_group_size_y
      - .offset:         160
        .size:           2
        .value_kind:     hidden_group_size_z
      - .offset:         162
        .size:           2
        .value_kind:     hidden_remainder_x
      - .offset:         164
        .size:           2
        .value_kind:     hidden_remainder_y
      - .offset:         166
        .size:           2
        .value_kind:     hidden_remainder_z
      - .offset:         184
        .size:           8
        .value_kind:     hidden_global_offset_x
      - .offset:         192
        .size:           8
        .value_kind:     hidden_global_offset_y
      - .offset:         200
        .size:           8
        .value_kind:     hidden_global_offset_z
      - .offset:         208
        .size:           2
        .value_kind:     hidden_grid_dims
      - .offset:         232
        .size:           8
        .value_kind:     hidden_multigrid_sync_arg
      - .offset:         264
        .size:           4
        .value_kind:     hidden_dynamic_lds_size
    .group_segment_fixed_size: 0
    .kernarg_segment_align: 8
    .kernarg_segment_size: 400
    .language:       OpenCL C
    .language_version:
      - 2
      - 0
    .max_flat_workgroup_size: 512
    .name:           _Z14fwd_megakernel6Params
    .private_segment_fixed_size: 0
    .sgpr_count:     108
    .sgpr_spill_count: 64
    .symbol:         _Z14fwd_megakernel6Params.kd
    .uniform_work_group_size: 1
    .uses_dynamic_stack: false
    .vgpr_count:     256
    .vgpr_spill_count: 0
    .wavefront_size: 64
